# v33 + loop-carried SALU of the attention loops moved ahead of the segment barrier's LDS-write wait (hidden under the ds_write latency), 3 sites
# speedup vs baseline: 1.0043x; 1.0001x over previous
.LBB0_520:
	s_min_i32 s2, s36, s34
	s_waitcnt vmcnt(4)
	ds_write_b128 v203, v[12:15] offset:32768
	s_waitcnt vmcnt(3)
	ds_write_b128 v203, v[146:149] offset:40960
	s_waitcnt vmcnt(2)
	ds_write_b128 v181, v[150:153]
	v_or_b32_e32 v12, s2, v171
	v_ashrrev_i32_e32 v13, 31, v12
	v_add_u32_e32 v14, s2, v190
	v_lshlrev_b64 v[12:13], 13, v[12:13]
	v_ashrrev_i32_e32 v15, 31, v14
	s_waitcnt lgkmcnt(0)
	s_barrier
	v_lshl_add_u64 v[12:13], v[186:187], 0, v[12:13]
	v_lshlrev_b64 v[14:15], 13, v[14:15]
	v_lshl_add_u64 v[14:15], v[186:187], 0, v[14:15]
	global_load_dwordx4 v[146:149], v[12:13], off
	global_load_dwordx4 v[150:153], v[14:15], off
	v_add_u32_e32 v12, s2, v173
	v_ashrrev_i32_e32 v13, 31, v12
	v_lshlrev_b64 v[12:13], 7, v[12:13]
	v_lshl_add_u64 v[12:13], v[188:189], 0, v[12:13]
	global_load_dwordx4 v[154:157], v[12:13], off
	v_fmamk_f32 v17, v98, 0x3dd53b94, v216
	v_fmamk_f32 v98, v99, 0x3dd53b94, v216
	v_exp_f32_e32 v17, v17
	v_fmamk_f32 v99, v100, 0x3dd53b94, v216
	v_fmamk_f32 v100, v101, 0x3dd53b94, v216
	v_fmamk_f32 v101, v102, 0x3dd53b94, v216
	v_fmamk_f32 v102, v103, 0x3dd53b94, v216
	v_fmamk_f32 v103, v104, 0x3dd53b94, v216
	v_fmamk_f32 v104, v105, 0x3dd53b94, v216
	v_fmamk_f32 v105, v106, 0x3dd53b94, v216
	v_fmamk_f32 v106, v107, 0x3dd53b94, v216
	v_fmamk_f32 v107, v108, 0x3dd53b94, v216
	v_fmamk_f32 v108, v109, 0x3dd53b94, v216
	v_fmamk_f32 v109, v110, 0x3dd53b94, v216
	v_fmamk_f32 v110, v111, 0x3dd53b94, v216
	v_fmamk_f32 v111, v112, 0x3dd53b94, v216
	v_fmamk_f32 v112, v113, 0x3dd53b94, v216
	v_fmamk_f32 v82, v82, 0x3dd53b94, v216
	v_fmamk_f32 v83, v83, 0x3dd53b94, v216
	v_fmamk_f32 v84, v84, 0x3dd53b94, v216
	v_fmamk_f32 v85, v85, 0x3dd53b94, v216
	v_fmamk_f32 v86, v86, 0x3dd53b94, v216
	v_fmamk_f32 v87, v87, 0x3dd53b94, v216
	v_fmamk_f32 v88, v88, 0x3dd53b94, v216
	v_fmamk_f32 v89, v89, 0x3dd53b94, v216
	v_fmamk_f32 v90, v90, 0x3dd53b94, v216
	v_fmamk_f32 v91, v91, 0x3dd53b94, v216
	v_fmamk_f32 v92, v92, 0x3dd53b94, v216
	v_fmamk_f32 v93, v93, 0x3dd53b94, v216
	v_fmamk_f32 v94, v94, 0x3dd53b94, v216
	v_fmamk_f32 v95, v95, 0x3dd53b94, v216
	v_fmamk_f32 v96, v96, 0x3dd53b94, v216
	v_fmac_f32_e32 v216, 0x3dd53b94, v97
	v_exp_f32_e32 v97, v98
	v_exp_f32_e32 v98, v99
	v_exp_f32_e32 v99, v100
	v_add_f32_e32 v12, v217, v218
	v_exp_f32_e32 v100, v101
	v_fmac_f32_e32 v12, v213, v2
	v_add_f32_e32 v2, 0, v17
	v_exp_f32_e32 v101, v102
	v_add_f32_e32 v2, v97, v2
	v_exp_f32_e32 v102, v103
	v_add_f32_e32 v2, v98, v2
	v_exp_f32_e32 v103, v104
	v_add_f32_e32 v2, v99, v2
	v_exp_f32_e32 v104, v105
	v_add_f32_e32 v2, v100, v2
	v_exp_f32_e32 v105, v106
	v_add_f32_e32 v2, v101, v2
	v_exp_f32_e32 v106, v107
	v_add_f32_e32 v2, v102, v2
	v_exp_f32_e32 v107, v108
	v_add_f32_e32 v2, v103, v2
	v_exp_f32_e32 v108, v109
	v_add_f32_e32 v2, v104, v2
	v_exp_f32_e32 v109, v110
	v_add_f32_e32 v2, v105, v2
	v_exp_f32_e32 v110, v111
	v_add_f32_e32 v2, v106, v2
	v_exp_f32_e32 v111, v112
	v_add_f32_e32 v2, v107, v2
	v_exp_f32_e32 v112, v82
	v_add_f32_e32 v2, v108, v2
	v_exp_f32_e32 v113, v83
	v_add_f32_e32 v2, v109, v2
	v_exp_f32_e32 v215, v84
	v_add_f32_e32 v2, v110, v2
	v_exp_f32_e32 v219, v85
	v_add_f32_e32 v2, v111, v2
	v_exp_f32_e32 v220, v86
	v_add_f32_e32 v2, v112, v2
	v_exp_f32_e32 v221, v87
	v_add_f32_e32 v2, v113, v2
	v_exp_f32_e32 v222, v88
	v_add_f32_e32 v2, v215, v2
	v_exp_f32_e32 v89, v89
	v_add_f32_e32 v2, v219, v2
	v_exp_f32_e32 v90, v90
	v_add_f32_e32 v2, v220, v2
	v_exp_f32_e32 v91, v91
	v_add_f32_e32 v2, v221, v2
	v_exp_f32_e32 v92, v92
	v_add_f32_e32 v2, v222, v2
	v_exp_f32_e32 v93, v93
	v_add_f32_e32 v2, v89, v2
	v_exp_f32_e32 v94, v94
	v_add_f32_e32 v2, v90, v2
	v_exp_f32_e32 v95, v95
	v_add_f32_e32 v2, v91, v2
	v_exp_f32_e32 v96, v96
	v_add_f32_e32 v2, v92, v2
	v_exp_f32_e32 v216, v216
	v_add_f32_e32 v2, v93, v2
	v_add_f32_e32 v2, v94, v2
	v_add_f32_e32 v2, v95, v2
	v_add_f32_e32 v2, v96, v2
	v_add_f32_e32 v2, v216, v2
	v_mov_b32_e32 v13, v2
	s_nop 1
	v_permlane32_swap_b32_e32 v2, v13
	v_add_f32_e32 v213, v2, v13
	s_add_i32 s2, s37, 2
	v_fmac_f32_e32 v213, v12, v16
	v_cvt_pk_bf16_f32 v12, v17, v97
	v_cvt_pk_bf16_f32 v13, v98, v99
	v_cvt_pk_bf16_f32 v14, v100, v101
	v_cvt_pk_bf16_f32 v15, v102, v103
	v_cvt_pk_bf16_f32 v82, v104, v105
	v_cvt_pk_bf16_f32 v83, v106, v107
	v_cvt_pk_bf16_f32 v84, v108, v109
	v_cvt_pk_bf16_f32 v85, v110, v111
	v_cvt_pk_bf16_f32 v86, v112, v113
	v_cvt_pk_bf16_f32 v87, v215, v219
	v_cvt_pk_bf16_f32 v88, v220, v221
	v_cvt_pk_bf16_f32 v89, v222, v89
	v_cvt_pk_bf16_f32 v90, v90, v91
	v_cvt_pk_bf16_f32 v91, v92, v93
	v_cvt_pk_bf16_f32 v92, v94, v95
	v_cvt_pk_bf16_f32 v93, v96, v216
	s_nop 0
	v_permlane32_swap_b32_e32 v12, v14
	v_permlane32_swap_b32_e32 v13, v15
	v_permlane32_swap_b32_e32 v82, v84
	v_permlane32_swap_b32_e32 v83, v85
	v_permlane32_swap_b32_e32 v86, v88
	v_permlane32_swap_b32_e32 v87, v89
	v_permlane32_swap_b32_e32 v90, v92
	v_permlane32_swap_b32_e32 v91, v93
	ds_read_b64_tr_b16 v[94:95], v191 offset:0x4000
	ds_read_b64_tr_b16 v[96:97], v191 offset:0x4800
	ds_read_b64_tr_b16 v[98:99], v191 offset:0x5000
	ds_read_b64_tr_b16 v[100:101], v191 offset:0x5800
	ds_read_b64_tr_b16 v[102:103], v191 offset:0x6000
	ds_read_b64_tr_b16 v[104:105], v191 offset:0x6800
	ds_read_b64_tr_b16 v[106:107], v191 offset:0x7000
	ds_read_b64_tr_b16 v[108:109], v191 offset:0x7800
	s_waitcnt lgkmcnt(0)
	s_nop 0
	v_mfma_f32_32x32x16_bf16 v[66:81], v[12:15], v[94:97], v[66:81]
	ds_read_b64_tr_b16 v[94:95], v191 offset:0x4200
	ds_read_b64_tr_b16 v[96:97], v191 offset:0x4a00
	v_mfma_f32_32x32x16_bf16 v[66:81], v[82:85], v[98:101], v[66:81]
	ds_read_b64_tr_b16 v[98:99], v191 offset:0x5200
	ds_read_b64_tr_b16 v[100:101], v191 offset:0x5a00
	v_mfma_f32_32x32x16_bf16 v[66:81], v[86:89], v[102:105], v[66:81]
	ds_read_b64_tr_b16 v[102:103], v191 offset:0x6200
	ds_read_b64_tr_b16 v[104:105], v191 offset:0x6a00
	ds_read_b64_tr_b16 v[110:111], v191 offset:0x7200
	ds_read_b64_tr_b16 v[112:113], v191 offset:0x7a00
	s_waitcnt lgkmcnt(0)
	v_mfma_f32_32x32x16_bf16 v[66:81], v[90:93], v[106:109], v[66:81]
	v_mfma_f32_32x32x16_bf16 v[50:65], v[12:15], v[94:97], v[50:65]
	ds_read_b64_tr_b16 v[94:95], v191 offset:0x4400
	ds_read_b64_tr_b16 v[96:97], v191 offset:0x4c00
	v_mfma_f32_32x32x16_bf16 v[50:65], v[82:85], v[98:101], v[50:65]
	ds_read_b64_tr_b16 v[98:99], v191 offset:0x5400
	ds_read_b64_tr_b16 v[100:101], v191 offset:0x5c00
	v_mfma_f32_32x32x16_bf16 v[50:65], v[86:89], v[102:105], v[50:65]
	ds_read_b64_tr_b16 v[102:103], v191 offset:0x6400
	ds_read_b64_tr_b16 v[104:105], v191 offset:0x6c00
	ds_read_b64_tr_b16 v[106:107], v191 offset:0x7400
	ds_read_b64_tr_b16 v[108:109], v191 offset:0x7c00
	s_waitcnt lgkmcnt(0)
	v_mfma_f32_32x32x16_bf16 v[50:65], v[90:93], v[110:113], v[50:65]
	v_mfma_f32_32x32x16_bf16 v[34:49], v[12:15], v[94:97], v[34:49]
	ds_read_b64_tr_b16 v[94:95], v191 offset:0x4600
	ds_read_b64_tr_b16 v[96:97], v191 offset:0x4e00
	v_mfma_f32_32x32x16_bf16 v[34:49], v[82:85], v[98:101], v[34:49]
	ds_read_b64_tr_b16 v[98:99], v191 offset:0x5600
	ds_read_b64_tr_b16 v[100:101], v191 offset:0x5e00
	v_mfma_f32_32x32x16_bf16 v[34:49], v[86:89], v[102:105], v[34:49]
	ds_read_b64_tr_b16 v[102:103], v191 offset:0x6600
	ds_read_b64_tr_b16 v[104:105], v191 offset:0x6e00
	ds_read_b64_tr_b16 v[110:111], v191 offset:0x7600
	ds_read_b64_tr_b16 v[112:113], v191 offset:0x7e00
	s_waitcnt lgkmcnt(0)
	v_mfma_f32_32x32x16_bf16 v[34:49], v[90:93], v[106:109], v[34:49]
	v_mfma_f32_32x32x16_bf16 v[18:33], v[12:15], v[94:97], v[18:33]
	s_waitcnt vmcnt(4)
	ds_write_b128 v205, v[8:11]
	s_waitcnt vmcnt(3)
	ds_write_b128 v206, v[4:7]
	s_add_i32 s18, s37, 3
	s_addk_i32 s36, 0x80
	s_waitcnt lgkmcnt(0)
	s_barrier
	v_mfma_f32_32x32x16_bf16 v[18:33], v[82:85], v[98:101], v[18:33]
	s_addk_i32 s35, 0xff80
	s_cmp_lt_u32 s18, s17
	v_mfma_f32_32x32x16_bf16 v[18:33], v[86:89], v[102:105], v[18:33]
	v_mfma_f32_32x32x16_bf16 v[18:33], v[90:93], v[110:113], v[18:33]
	s_cbranch_scc0 .LBB0_524
	s_mov_b32 s37, s2
	s_branch .LBB0_505

.LBB0_1755:
	s_add_i32 s8, s22, 0xc0
	s_min_i32 s22, s8, s20
	s_waitcnt vmcnt(3)
	ds_write_b128 v188, v[12:15] offset:32768
	s_waitcnt vmcnt(2)
	ds_write_b128 v188, v[146:149] offset:40960
	v_or_b32_e32 v12, s22, v178
	s_waitcnt lgkmcnt(0)
	s_barrier
	v_mad_i64_i32 v[12:13], s[8:9], v12, s3, v[164:165]
	v_add_u32_e32 v14, s22, v179
	v_mad_i64_i32 v[14:15], s[8:9], v14, s3, v[164:165]
	global_load_dwordx4 v[146:149], v[12:13], off
	global_load_dwordx4 v[150:153], v[14:15], off
	v_fmamk_f32 v98, v98, 0x3e0293ee, v17
	v_fmamk_f32 v99, v99, 0x3e0293ee, v17
	v_fmamk_f32 v100, v100, 0x3e0293ee, v17
	v_fmamk_f32 v101, v101, 0x3e0293ee, v17
	v_fmamk_f32 v102, v102, 0x3e0293ee, v17
	v_fmamk_f32 v103, v103, 0x3e0293ee, v17
	v_fmamk_f32 v104, v104, 0x3e0293ee, v17
	v_fmamk_f32 v105, v105, 0x3e0293ee, v17
	v_fmamk_f32 v106, v106, 0x3e0293ee, v17
	v_fmamk_f32 v107, v107, 0x3e0293ee, v17
	v_fmamk_f32 v108, v108, 0x3e0293ee, v17
	v_fmamk_f32 v109, v109, 0x3e0293ee, v17
	v_fmamk_f32 v110, v110, 0x3e0293ee, v17
	v_fmamk_f32 v111, v111, 0x3e0293ee, v17
	v_fmamk_f32 v112, v112, 0x3e0293ee, v17
	v_fmamk_f32 v113, v113, 0x3e0293ee, v17
	v_fmamk_f32 v82, v82, 0x3e0293ee, v17
	v_fmamk_f32 v83, v83, 0x3e0293ee, v17
	v_fmamk_f32 v84, v84, 0x3e0293ee, v17
	v_fmamk_f32 v85, v85, 0x3e0293ee, v17
	v_fmamk_f32 v86, v86, 0x3e0293ee, v17
	v_fmamk_f32 v87, v87, 0x3e0293ee, v17
	v_fmamk_f32 v88, v88, 0x3e0293ee, v17
	v_fmamk_f32 v89, v89, 0x3e0293ee, v17
	v_fmamk_f32 v90, v90, 0x3e0293ee, v17
	v_fmamk_f32 v91, v91, 0x3e0293ee, v17
	v_fmamk_f32 v92, v92, 0x3e0293ee, v17
	v_fmamk_f32 v93, v93, 0x3e0293ee, v17
	v_fmamk_f32 v94, v94, 0x3e0293ee, v17
	v_fmamk_f32 v95, v95, 0x3e0293ee, v17
	v_fmamk_f32 v96, v96, 0x3e0293ee, v17
	v_fmac_f32_e32 v17, 0x3e0293ee, v97
	v_exp_f32_e32 v97, v98
	v_exp_f32_e32 v98, v99
	v_exp_f32_e32 v99, v100
	v_exp_f32_e32 v100, v101
	v_add_f32_e32 v12, v169, v174
	v_exp_f32_e32 v101, v102
	v_fmac_f32_e32 v12, v161, v2
	v_add_f32_e32 v2, 0, v97
	v_exp_f32_e32 v102, v103
	v_add_f32_e32 v2, v98, v2
	v_exp_f32_e32 v103, v104
	v_add_f32_e32 v2, v99, v2
	v_exp_f32_e32 v104, v105
	v_add_f32_e32 v2, v100, v2
	v_exp_f32_e32 v105, v106
	v_add_f32_e32 v2, v101, v2
	v_exp_f32_e32 v106, v107
	v_add_f32_e32 v2, v102, v2
	v_exp_f32_e32 v107, v108
	v_add_f32_e32 v2, v103, v2
	v_exp_f32_e32 v108, v109
	v_add_f32_e32 v2, v104, v2
	v_exp_f32_e32 v109, v110
	v_add_f32_e32 v2, v105, v2
	v_exp_f32_e32 v110, v111
	v_add_f32_e32 v2, v106, v2
	v_exp_f32_e32 v111, v112
	v_add_f32_e32 v2, v107, v2
	v_exp_f32_e32 v112, v113
	v_add_f32_e32 v2, v108, v2
	v_exp_f32_e32 v113, v82
	v_add_f32_e32 v2, v109, v2
	v_exp_f32_e32 v175, v83
	v_add_f32_e32 v2, v110, v2
	v_exp_f32_e32 v195, v84
	v_add_f32_e32 v2, v111, v2
	v_exp_f32_e32 v196, v85
	v_add_f32_e32 v2, v112, v2
	v_exp_f32_e32 v197, v86
	v_add_f32_e32 v2, v113, v2
	v_exp_f32_e32 v198, v87
	v_add_f32_e32 v2, v175, v2
	v_exp_f32_e32 v199, v88
	v_add_f32_e32 v2, v195, v2
	v_exp_f32_e32 v89, v89
	v_add_f32_e32 v2, v196, v2
	v_exp_f32_e32 v90, v90
	v_add_f32_e32 v2, v197, v2
	v_exp_f32_e32 v91, v91
	v_add_f32_e32 v2, v198, v2
	v_exp_f32_e32 v92, v92
	v_add_f32_e32 v2, v199, v2
	v_exp_f32_e32 v93, v93
	v_add_f32_e32 v2, v89, v2
	v_exp_f32_e32 v94, v94
	v_add_f32_e32 v2, v90, v2
	v_exp_f32_e32 v95, v95
	v_add_f32_e32 v2, v91, v2
	v_exp_f32_e32 v96, v96
	v_add_f32_e32 v2, v92, v2
	v_exp_f32_e32 v17, v17
	v_add_f32_e32 v2, v93, v2
	v_add_f32_e32 v2, v94, v2
	v_add_f32_e32 v2, v95, v2
	v_add_f32_e32 v2, v96, v2
	v_add_f32_e32 v2, v17, v2
	v_mov_b32_e32 v13, v2
	s_nop 1
	v_permlane32_swap_b32_e32 v2, v13
	v_add_f32_e32 v161, v2, v13
	s_add_i32 s8, s21, 2
	v_fmac_f32_e32 v161, v12, v16
	v_cvt_pk_bf16_f32 v12, v97, v98
	v_cvt_pk_bf16_f32 v13, v99, v100
	v_cvt_pk_bf16_f32 v14, v101, v102
	v_cvt_pk_bf16_f32 v15, v103, v104
	v_cvt_pk_bf16_f32 v82, v105, v106
	v_cvt_pk_bf16_f32 v83, v107, v108
	v_cvt_pk_bf16_f32 v84, v109, v110
	v_cvt_pk_bf16_f32 v85, v111, v112
	v_cvt_pk_bf16_f32 v86, v113, v175
	v_cvt_pk_bf16_f32 v87, v195, v196
	v_cvt_pk_bf16_f32 v88, v197, v198
	v_cvt_pk_bf16_f32 v89, v199, v89
	v_cvt_pk_bf16_f32 v90, v90, v91
	v_cvt_pk_bf16_f32 v91, v92, v93
	v_cvt_pk_bf16_f32 v92, v94, v95
	v_cvt_pk_bf16_f32 v93, v96, v17
	s_nop 0
	v_permlane32_swap_b32_e32 v12, v14
	v_permlane32_swap_b32_e32 v13, v15
	v_permlane32_swap_b32_e32 v82, v84
	v_permlane32_swap_b32_e32 v83, v85
	v_permlane32_swap_b32_e32 v86, v88
	v_permlane32_swap_b32_e32 v87, v89
	v_permlane32_swap_b32_e32 v90, v92
	v_permlane32_swap_b32_e32 v91, v93
	ds_read_b64_tr_b16 v[94:95], v180 offset:0x4000
	ds_read_b64_tr_b16 v[96:97], v180 offset:0x4800
	ds_read_b64_tr_b16 v[98:99], v180 offset:0x5000
	ds_read_b64_tr_b16 v[100:101], v180 offset:0x5800
	ds_read_b64_tr_b16 v[102:103], v180 offset:0x6000
	ds_read_b64_tr_b16 v[104:105], v180 offset:0x6800
	ds_read_b64_tr_b16 v[106:107], v180 offset:0x7000
	ds_read_b64_tr_b16 v[108:109], v180 offset:0x7800
	ds_read_b64_tr_b16 v[110:111], v180 offset:0x4200
	ds_read_b64_tr_b16 v[112:113], v180 offset:0x4a00
	ds_read_b64_tr_b16 v[196:197], v180 offset:0x5200
	ds_read_b64_tr_b16 v[198:199], v180 offset:0x5a00
	ds_read_b64_tr_b16 v[200:201], v180 offset:0x6200
	ds_read_b64_tr_b16 v[202:203], v180 offset:0x6a00
	ds_read_b64_tr_b16 v[204:205], v180 offset:0x7200
	ds_read_b64_tr_b16 v[206:207], v180 offset:0x7a00
	s_waitcnt lgkmcnt(8)
	s_nop 0
	v_mfma_f32_32x32x16_bf16 v[66:81], v[12:15], v[94:97], v[66:81]
	ds_read_b64_tr_b16 v[94:95], v180 offset:0x4400
	ds_read_b64_tr_b16 v[96:97], v180 offset:0x4c00
	v_mfma_f32_32x32x16_bf16 v[66:81], v[82:85], v[98:101], v[66:81]
	ds_read_b64_tr_b16 v[98:99], v180 offset:0x5400
	ds_read_b64_tr_b16 v[100:101], v180 offset:0x5c00
	v_mfma_f32_32x32x16_bf16 v[66:81], v[86:89], v[102:105], v[66:81]
	ds_read_b64_tr_b16 v[102:103], v180 offset:0x6400
	ds_read_b64_tr_b16 v[104:105], v180 offset:0x6c00
	ds_read_b64_tr_b16 v[208:209], v180 offset:0x7400
	ds_read_b64_tr_b16 v[210:211], v180 offset:0x7c00
	s_waitcnt lgkmcnt(8)
	v_mfma_f32_32x32x16_bf16 v[66:81], v[90:93], v[106:109], v[66:81]
	v_mfma_f32_32x32x16_bf16 v[50:65], v[12:15], v[110:113], v[50:65]
	ds_read_b64_tr_b16 v[106:107], v180 offset:0x4600
	ds_read_b64_tr_b16 v[108:109], v180 offset:0x4e00
	ds_read_b64_tr_b16 v[110:111], v180 offset:0x5600
	ds_read_b64_tr_b16 v[112:113], v180 offset:0x5e00
	v_mfma_f32_32x32x16_bf16 v[50:65], v[82:85], v[196:199], v[50:65]
	ds_read_b64_tr_b16 v[196:197], v180 offset:0x6600
	ds_read_b64_tr_b16 v[198:199], v180 offset:0x6e00
	v_mfma_f32_32x32x16_bf16 v[50:65], v[86:89], v[200:203], v[50:65]
	ds_read_b64_tr_b16 v[200:201], v180 offset:0x7600
	ds_read_b64_tr_b16 v[202:203], v180 offset:0x7e00
	s_waitcnt lgkmcnt(8)
	v_mfma_f32_32x32x16_bf16 v[50:65], v[90:93], v[204:207], v[50:65]
	v_mfma_f32_32x32x16_bf16 v[34:49], v[12:15], v[94:97], v[34:49]
	s_waitcnt lgkmcnt(0)
	v_mfma_f32_32x32x16_bf16 v[34:49], v[82:85], v[98:101], v[34:49]
	v_mfma_f32_32x32x16_bf16 v[34:49], v[86:89], v[102:105], v[34:49]
	v_mfma_f32_32x32x16_bf16 v[34:49], v[90:93], v[208:211], v[34:49]
	v_mfma_f32_32x32x16_bf16 v[18:33], v[12:15], v[106:109], v[18:33]
	s_waitcnt vmcnt(3)
	ds_write_b128 v189, v[4:7]
	s_waitcnt vmcnt(2)
	ds_write_b128 v190, v[8:11]
	s_add_i32 s9, s21, 3
	s_addk_i32 s11, 0xff80
	s_cmp_lt_i32 s9, s19
	s_waitcnt lgkmcnt(0)
	s_barrier
	v_mfma_f32_32x32x16_bf16 v[18:33], v[82:85], v[110:113], v[18:33]
	v_mfma_f32_32x32x16_bf16 v[18:33], v[86:89], v[196:199], v[18:33]
	v_mfma_f32_32x32x16_bf16 v[18:33], v[90:93], v[200:203], v[18:33]
	s_cbranch_scc0 .LBB0_1761
	s_mov_b32 s22, s2
	s_mov_b32 s21, s8
	s_branch .LBB0_1740

.LBB0_1907:
	s_add_i32 s2, s10, 1
	v_lshrrev_b64 v[150:151], s2, v[164:165]
	s_min_i32 s2, s18, s5
	s_waitcnt vmcnt(3)
	ds_write_b128 v188, v[12:15] offset:32768
	s_waitcnt vmcnt(2)
	ds_write_b128 v188, v[146:149] offset:40960
	v_or_b32_e32 v12, s2, v178
	v_and_b32_e32 v150, 1, v150
	s_waitcnt lgkmcnt(0)
	s_barrier
	v_mad_i64_i32 v[12:13], s[12:13], v12, s3, v[168:169]
	v_add_u32_e32 v14, s2, v179
	v_cmp_eq_u32_e32 vcc, 1, v150
	v_mad_i64_i32 v[14:15], s[12:13], v14, s3, v[168:169]
	global_load_dwordx4 v[146:149], v[12:13], off
	global_load_dwordx4 v[150:153], v[14:15], off
	v_cndmask_b32_e32 v17, v191, v17, vcc
	v_fmamk_f32 v98, v98, 0x3e0293ee, v17
	v_fmamk_f32 v99, v99, 0x3e0293ee, v17
	v_fmamk_f32 v100, v100, 0x3e0293ee, v17
	v_fmamk_f32 v101, v101, 0x3e0293ee, v17
	v_fmamk_f32 v102, v102, 0x3e0293ee, v17
	v_fmamk_f32 v103, v103, 0x3e0293ee, v17
	v_fmamk_f32 v104, v104, 0x3e0293ee, v17
	v_fmamk_f32 v105, v105, 0x3e0293ee, v17
	v_fmamk_f32 v106, v106, 0x3e0293ee, v17
	v_fmamk_f32 v107, v107, 0x3e0293ee, v17
	v_fmamk_f32 v108, v108, 0x3e0293ee, v17
	v_fmamk_f32 v109, v109, 0x3e0293ee, v17
	v_fmamk_f32 v110, v110, 0x3e0293ee, v17
	v_fmamk_f32 v111, v111, 0x3e0293ee, v17
	v_fmamk_f32 v112, v112, 0x3e0293ee, v17
	v_fmamk_f32 v113, v113, 0x3e0293ee, v17
	v_fmamk_f32 v82, v82, 0x3e0293ee, v17
	v_fmamk_f32 v83, v83, 0x3e0293ee, v17
	v_fmamk_f32 v84, v84, 0x3e0293ee, v17
	v_fmamk_f32 v85, v85, 0x3e0293ee, v17
	v_fmamk_f32 v86, v86, 0x3e0293ee, v17
	v_fmamk_f32 v87, v87, 0x3e0293ee, v17
	v_fmamk_f32 v88, v88, 0x3e0293ee, v17
	v_fmamk_f32 v89, v89, 0x3e0293ee, v17
	v_fmamk_f32 v90, v90, 0x3e0293ee, v17
	v_fmamk_f32 v91, v91, 0x3e0293ee, v17
	v_fmamk_f32 v92, v92, 0x3e0293ee, v17
	v_fmamk_f32 v93, v93, 0x3e0293ee, v17
	v_fmamk_f32 v94, v94, 0x3e0293ee, v17
	v_fmamk_f32 v95, v95, 0x3e0293ee, v17
	v_fmamk_f32 v96, v96, 0x3e0293ee, v17
	v_fmac_f32_e32 v17, 0x3e0293ee, v97
	v_exp_f32_e32 v97, v98
	v_exp_f32_e32 v98, v99
	v_exp_f32_e32 v99, v100
	v_exp_f32_e32 v100, v101
	v_add_f32_e32 v12, v175, v195
	v_exp_f32_e32 v101, v102
	v_fmac_f32_e32 v12, v159, v2
	v_add_f32_e32 v2, 0, v97
	v_exp_f32_e32 v102, v103
	v_add_f32_e32 v2, v98, v2
	v_exp_f32_e32 v103, v104
	v_add_f32_e32 v2, v99, v2
	v_exp_f32_e32 v104, v105
	v_add_f32_e32 v2, v100, v2
	v_exp_f32_e32 v105, v106
	v_add_f32_e32 v2, v101, v2
	v_exp_f32_e32 v106, v107
	v_add_f32_e32 v2, v102, v2
	v_exp_f32_e32 v107, v108
	v_add_f32_e32 v2, v103, v2
	v_exp_f32_e32 v108, v109
	v_add_f32_e32 v2, v104, v2
	v_exp_f32_e32 v109, v110
	v_add_f32_e32 v2, v105, v2
	v_exp_f32_e32 v110, v111
	v_add_f32_e32 v2, v106, v2
	v_exp_f32_e32 v111, v112
	v_add_f32_e32 v2, v107, v2
	v_exp_f32_e32 v112, v113
	v_add_f32_e32 v2, v108, v2
	v_exp_f32_e32 v113, v82
	v_add_f32_e32 v2, v109, v2
	v_exp_f32_e32 v196, v83
	v_add_f32_e32 v2, v110, v2
	v_exp_f32_e32 v197, v84
	v_add_f32_e32 v2, v111, v2
	v_exp_f32_e32 v198, v85
	v_add_f32_e32 v2, v112, v2
	v_exp_f32_e32 v199, v86
	v_add_f32_e32 v2, v113, v2
	v_exp_f32_e32 v200, v87
	v_add_f32_e32 v2, v196, v2
	v_exp_f32_e32 v201, v88
	v_add_f32_e32 v2, v197, v2
	v_exp_f32_e32 v89, v89
	v_add_f32_e32 v2, v198, v2
	v_exp_f32_e32 v90, v90
	v_add_f32_e32 v2, v199, v2
	v_exp_f32_e32 v91, v91
	v_add_f32_e32 v2, v200, v2
	v_exp_f32_e32 v92, v92
	v_add_f32_e32 v2, v201, v2
	v_exp_f32_e32 v93, v93
	v_add_f32_e32 v2, v89, v2
	v_exp_f32_e32 v94, v94
	v_add_f32_e32 v2, v90, v2
	v_exp_f32_e32 v95, v95
	v_add_f32_e32 v2, v91, v2
	v_exp_f32_e32 v96, v96
	v_add_f32_e32 v2, v92, v2
	v_exp_f32_e32 v17, v17
	v_add_f32_e32 v2, v93, v2
	v_add_f32_e32 v2, v94, v2
	v_add_f32_e32 v2, v95, v2
	v_add_f32_e32 v2, v96, v2
	v_add_f32_e32 v2, v17, v2
	v_mov_b32_e32 v13, v2
	s_nop 1
	v_permlane32_swap_b32_e32 v2, v13
	v_add_f32_e32 v159, v2, v13
	v_fmac_f32_e32 v159, v12, v16
	v_cvt_pk_bf16_f32 v12, v97, v98
	v_cvt_pk_bf16_f32 v13, v99, v100
	v_cvt_pk_bf16_f32 v14, v101, v102
	v_cvt_pk_bf16_f32 v15, v103, v104
	v_cvt_pk_bf16_f32 v82, v105, v106
	v_cvt_pk_bf16_f32 v83, v107, v108
	v_cvt_pk_bf16_f32 v84, v109, v110
	v_cvt_pk_bf16_f32 v85, v111, v112
	v_cvt_pk_bf16_f32 v86, v113, v196
	v_cvt_pk_bf16_f32 v87, v197, v198
	v_cvt_pk_bf16_f32 v88, v199, v200
	v_cvt_pk_bf16_f32 v89, v201, v89
	v_cvt_pk_bf16_f32 v90, v90, v91
	v_cvt_pk_bf16_f32 v91, v92, v93
	v_cvt_pk_bf16_f32 v92, v94, v95
	v_cvt_pk_bf16_f32 v93, v96, v17
	s_nop 0
	v_permlane32_swap_b32_e32 v12, v14
	v_permlane32_swap_b32_e32 v13, v15
	v_permlane32_swap_b32_e32 v82, v84
	v_permlane32_swap_b32_e32 v83, v85
	v_permlane32_swap_b32_e32 v86, v88
	v_permlane32_swap_b32_e32 v87, v89
	v_permlane32_swap_b32_e32 v90, v92
	v_permlane32_swap_b32_e32 v91, v93
	ds_read_b64_tr_b16 v[94:95], v180 offset:0x4000
	ds_read_b64_tr_b16 v[96:97], v180 offset:0x4800
	ds_read_b64_tr_b16 v[98:99], v180 offset:0x5000
	ds_read_b64_tr_b16 v[100:101], v180 offset:0x5800
	ds_read_b64_tr_b16 v[102:103], v180 offset:0x6000
	ds_read_b64_tr_b16 v[104:105], v180 offset:0x6800
	ds_read_b64_tr_b16 v[106:107], v180 offset:0x7000
	ds_read_b64_tr_b16 v[108:109], v180 offset:0x7800
	ds_read_b64_tr_b16 v[110:111], v180 offset:0x4200
	ds_read_b64_tr_b16 v[112:113], v180 offset:0x4a00
	ds_read_b64_tr_b16 v[196:197], v180 offset:0x5200
	ds_read_b64_tr_b16 v[198:199], v180 offset:0x5a00
	ds_read_b64_tr_b16 v[200:201], v180 offset:0x6200
	ds_read_b64_tr_b16 v[202:203], v180 offset:0x6a00
	ds_read_b64_tr_b16 v[204:205], v180 offset:0x7200
	ds_read_b64_tr_b16 v[206:207], v180 offset:0x7a00
	s_waitcnt lgkmcnt(8)
	s_nop 0
	v_mfma_f32_32x32x16_bf16 v[66:81], v[12:15], v[94:97], v[66:81]
	ds_read_b64_tr_b16 v[94:95], v180 offset:0x4400
	ds_read_b64_tr_b16 v[96:97], v180 offset:0x4c00
	v_mfma_f32_32x32x16_bf16 v[66:81], v[82:85], v[98:101], v[66:81]
	ds_read_b64_tr_b16 v[98:99], v180 offset:0x5400
	ds_read_b64_tr_b16 v[100:101], v180 offset:0x5c00
	v_mfma_f32_32x32x16_bf16 v[66:81], v[86:89], v[102:105], v[66:81]
	ds_read_b64_tr_b16 v[102:103], v180 offset:0x6400
	ds_read_b64_tr_b16 v[104:105], v180 offset:0x6c00
	ds_read_b64_tr_b16 v[208:209], v180 offset:0x7400
	ds_read_b64_tr_b16 v[210:211], v180 offset:0x7c00
	s_waitcnt lgkmcnt(8)
	v_mfma_f32_32x32x16_bf16 v[66:81], v[90:93], v[106:109], v[66:81]
	v_mfma_f32_32x32x16_bf16 v[50:65], v[12:15], v[110:113], v[50:65]
	ds_read_b64_tr_b16 v[106:107], v180 offset:0x4600
	ds_read_b64_tr_b16 v[108:109], v180 offset:0x4e00
	ds_read_b64_tr_b16 v[110:111], v180 offset:0x5600
	ds_read_b64_tr_b16 v[112:113], v180 offset:0x5e00
	v_mfma_f32_32x32x16_bf16 v[50:65], v[82:85], v[196:199], v[50:65]
	ds_read_b64_tr_b16 v[196:197], v180 offset:0x6600
	ds_read_b64_tr_b16 v[198:199], v180 offset:0x6e00
	v_mfma_f32_32x32x16_bf16 v[50:65], v[86:89], v[200:203], v[50:65]
	ds_read_b64_tr_b16 v[200:201], v180 offset:0x7600
	ds_read_b64_tr_b16 v[202:203], v180 offset:0x7e00
	s_waitcnt lgkmcnt(8)
	v_mfma_f32_32x32x16_bf16 v[50:65], v[90:93], v[204:207], v[50:65]
	v_mfma_f32_32x32x16_bf16 v[34:49], v[12:15], v[94:97], v[34:49]
	s_waitcnt lgkmcnt(0)
	v_mfma_f32_32x32x16_bf16 v[34:49], v[82:85], v[98:101], v[34:49]
	v_mfma_f32_32x32x16_bf16 v[34:49], v[86:89], v[102:105], v[34:49]
	v_mfma_f32_32x32x16_bf16 v[34:49], v[90:93], v[208:211], v[34:49]
	v_mfma_f32_32x32x16_bf16 v[18:33], v[12:15], v[106:109], v[18:33]
	s_waitcnt vmcnt(3)
	ds_write_b128 v189, v[4:7]
	s_waitcnt vmcnt(2)
	ds_write_b128 v190, v[8:11]
	s_add_u32 s10, s10, 2
	s_addc_u32 s11, s11, 0
	s_addk_i32 s18, 0x80
	s_waitcnt lgkmcnt(0)
	s_barrier
	v_mfma_f32_32x32x16_bf16 v[18:33], v[82:85], v[110:113], v[18:33]
	s_addk_i32 s17, 0xff80
	s_cmp_lt_u32 s10, s14
	v_mfma_f32_32x32x16_bf16 v[18:33], v[86:89], v[196:199], v[18:33]
	v_mfma_f32_32x32x16_bf16 v[18:33], v[90:93], v[200:203], v[18:33]
	s_cbranch_scc0 .LBB0_1925
